# diff-attention softmax block: V-fragment address math + 16 tr reads issued under the MFMA->VALU wait states before the row-max chain (s_nop padding removed)
# speedup vs baseline: 1.0103x; 1.0032x over previous
; #define LAS __attribute__((address_space(3)))
; template <bool DIFF> ...
;     ...
;                 c0 = sl2 * (float)(64 * kt - wrow); c1 = sl2 * (float)(64 * kt + 32 - wrow);
;                 if (64 * kt + 64 > wrow) {
;                     asm volatile("" ::: "memory");
;                     const int irel = wrow + l32 - 64 * kt - hi * 4;
; #pragma unroll
;                     for (int r = 0; r < 16; ++r) { const int cr = (r >> 2) * 8 + (r & 3); if (cr > irel) s0[r] = -INFINITY; if (cr + 32 > irel) s1[r] = -INFINITY; }
;                 }
;             }
;             LAS const unsigned char* va = vb + (hi * 4 + ((lane & 15) >> 2)) * VSTR + (DIFF ? 0 : c * 256) + (((lane >> 4) & 1) * 16 + 4 * (lane & 3)) * 2;
;             bf16x8 fa[4], fb[4];
;             const int vq = (lane & 15) >> 2, vp = lane & 3, vg1 = (lane >> 4) & 1;
;             const int vs0 = 256 * (hi * 4 + vq) + 16 * ((2 * vg1 + (vp >> 1)) ^ hi) + 8 * (vp & 1), vs1 = 256 * (hi * 4 + 8 + vq) + 16 * ((2 * vg1 + (vp >> 1)) ^ (hi + 2)) + 8 * (vp & 1);
;     ...
;             float mx0 = s0[0], mx1 = s1[0];
; #pragma unroll
;             for (int r = 1; r < 16; r += 2) { mx0 = fmaxf(fmaxf(mx0, s0[r]), s0[r + 1 < 16 ? r + 1 : r]); mx1 = fmaxf(fmaxf(mx1, s1[r]), s1[r + 1 < 16 ? r + 1 : r]); }
;             float mx = fmaxf(__builtin_fmaf(mx0, sc2, c0), __builtin_fmaf(mx1, sc2, c1));
;             mx = fmaxf(mx, __shfl_xor(mx, 32));
;             __builtin_amdgcn_sched_barrier(0);
;             ATT_LOADG(fa, 0); ATT_LOADG(fb, 1);
;             __builtin_amdgcn_sched_barrier(0);
;             if (__builtin_amdgcn_ballot_w64(mx > m_run) != 0ull) {
;                 const float mnew = fmaxf(m_run, mx), alpha = __builtin_amdgcn_exp2f(m_run - mnew); m_run = mnew; l_run *= alpha;
; #pragma unroll
;                 for (int i = 0; i < 4; ++i)
; #pragma unroll
;                     for (int r = 0; r < 16; ++r) o[i][r] *= alpha;
;             }
.LBB0_119:
	s_add_i32 s0, s24, s22
	s_add_i32 s1, s0, 64
	s_addk_i32 s0, 0x60
	v_cvt_f32_i32_e32 v218, s1
	v_cvt_f32_i32_e32 v219, s0
	v_add_u32_e32 v130, s23, v186
	v_add_u32_e32 v131, s23, v198
	v_add3_u32 v210, v130, v163, v197
	v_add3_u32 v211, v131, v163, v197
	v_add_u32_e32 v228, v210, v199
	v_add_u32_e32 v229, v211, v199
	v_add_u32_e32 v230, v210, v206
	v_add_u32_e32 v231, v211, v206
	v_add_u32_e32 v232, v210, v207
	v_add_u32_e32 v233, v211, v207
	v_add_u32_e32 v234, v210, v208
	v_add_u32_e32 v235, v211, v208
	ds_read_b64_tr_b16 v[130:131], v228 offset:16384
	ds_read_b64_tr_b16 v[132:133], v229 offset:18432
	ds_read_b64_tr_b16 v[134:135], v230 offset:16384
	ds_read_b64_tr_b16 v[136:137], v231 offset:18432
	ds_read_b64_tr_b16 v[138:139], v232 offset:16384
	ds_read_b64_tr_b16 v[140:141], v233 offset:18432
	ds_read_b64_tr_b16 v[142:143], v234 offset:16384
	ds_read_b64_tr_b16 v[144:145], v235 offset:18432
	ds_read_b64_tr_b16 v[146:147], v228 offset:20480
	ds_read_b64_tr_b16 v[148:149], v229 offset:22528
	ds_read_b64_tr_b16 v[150:151], v230 offset:20480
	ds_read_b64_tr_b16 v[152:153], v231 offset:22528
	ds_read_b64_tr_b16 v[154:155], v232 offset:20480
	ds_read_b64_tr_b16 v[156:157], v233 offset:22528
	ds_read_b64_tr_b16 v[158:159], v234 offset:20480
	ds_read_b64_tr_b16 v[160:161], v235 offset:22528
	v_max_f32_e32 v220, v82, v82
	v_mul_f32_e32 v212, v182, v218
	v_mul_f32_e32 v213, v182, v219
	v_max_f32_e32 v218, v99, v99
	v_max_f32_e32 v219, v98, v98
	v_max_f32_e32 v218, v219, v218
	v_max_f32_e32 v219, v83, v83
	v_max_f32_e32 v219, v220, v219
	v_max3_f32 v218, v218, v100, v101
	v_max3_f32 v219, v219, v84, v85
	v_max3_f32 v218, v218, v102, v103
	v_max3_f32 v219, v219, v86, v87
	v_max3_f32 v218, v218, v104, v105
	v_max3_f32 v219, v219, v88, v89
	v_max3_f32 v218, v218, v106, v107
	v_max3_f32 v219, v219, v90, v91
	v_max3_f32 v218, v218, v108, v109
	v_max3_f32 v219, v219, v92, v93
	v_max3_f32 v218, v218, v110, v111
	v_max3_f32 v219, v219, v94, v95
	v_max3_f32 v218, v218, v112, v113
	v_max3_f32 v219, v219, v96, v97
	v_fmamk_f32 v218, v218, 0x3e38aa3b, v212
	v_fmamk_f32 v219, v219, 0x3e38aa3b, v213
	v_max_f32_e32 v214, v218, v219
	v_mov_b32_e32 v215, v214
	v_mov_b32_e32 v216, v214
	s_nop 1
	v_permlane32_swap_b32_e32 v215, v216
	s_nop 1
	v_max_f32_e32 v214, v215, v216
	v_cmp_gt_f32_e32 vcc, v214, v209
	s_cbranch_vccz .LBB0_112
	v_max_f32_e32 v214, v214, v214
	v_max_f32_e32 v215, v209, v209
	v_max_f32_e32 v215, v215, v214
	v_sub_f32_e32 v209, v209, v215
	v_exp_f32_e32 v214, v209
	v_mov_b32_e32 v209, v215
	v_pk_mul_f32 v[64:65], v[64:65], v[214:215] op_sel_hi:[1,0]
	v_pk_mul_f32 v[62:63], v[62:63], v[214:215] op_sel_hi:[1,0]
	v_pk_mul_f32 v[60:61], v[60:61], v[214:215] op_sel_hi:[1,0]
	v_pk_mul_f32 v[58:59], v[58:59], v[214:215] op_sel_hi:[1,0]
	v_pk_mul_f32 v[56:57], v[56:57], v[214:215] op_sel_hi:[1,0]
	v_pk_mul_f32 v[54:55], v[54:55], v[214:215] op_sel_hi:[1,0]
	v_pk_mul_f32 v[52:53], v[52:53], v[214:215] op_sel_hi:[1,0]
	v_pk_mul_f32 v[50:51], v[50:51], v[214:215] op_sel_hi:[1,0]
	v_pk_mul_f32 v[48:49], v[48:49], v[214:215] op_sel_hi:[1,0]
	v_pk_mul_f32 v[46:47], v[46:47], v[214:215] op_sel_hi:[1,0]
	v_pk_mul_f32 v[44:45], v[44:45], v[214:215] op_sel_hi:[1,0]
	v_pk_mul_f32 v[42:43], v[42:43], v[214:215] op_sel_hi:[1,0]
	v_pk_mul_f32 v[40:41], v[40:41], v[214:215] op_sel_hi:[1,0]
	v_pk_mul_f32 v[38:39], v[38:39], v[214:215] op_sel_hi:[1,0]
	v_pk_mul_f32 v[36:37], v[36:37], v[214:215] op_sel_hi:[1,0]
	v_pk_mul_f32 v[34:35], v[34:35], v[214:215] op_sel_hi:[1,0]
	v_pk_mul_f32 v[32:33], v[32:33], v[214:215] op_sel_hi:[1,0]
	v_pk_mul_f32 v[30:31], v[30:31], v[214:215] op_sel_hi:[1,0]
	v_pk_mul_f32 v[28:29], v[28:29], v[214:215] op_sel_hi:[1,0]
	v_pk_mul_f32 v[26:27], v[26:27], v[214:215] op_sel_hi:[1,0]
	v_pk_mul_f32 v[24:25], v[24:25], v[214:215] op_sel_hi:[1,0]
	v_pk_mul_f32 v[22:23], v[22:23], v[214:215] op_sel_hi:[1,0]
	v_pk_mul_f32 v[20:21], v[20:21], v[214:215] op_sel_hi:[1,0]
	v_pk_mul_f32 v[18:19], v[18:19], v[214:215] op_sel_hi:[1,0]
	v_pk_mul_f32 v[16:17], v[16:17], v[214:215] op_sel_hi:[1,0]
	v_pk_mul_f32 v[14:15], v[14:15], v[214:215] op_sel_hi:[1,0]
	v_pk_mul_f32 v[12:13], v[12:13], v[214:215] op_sel_hi:[1,0]
	v_pk_mul_f32 v[10:11], v[10:11], v[214:215] op_sel_hi:[1,0]
	v_pk_mul_f32 v[8:9], v[8:9], v[214:215] op_sel_hi:[1,0]
	v_pk_mul_f32 v[6:7], v[6:7], v[214:215] op_sel_hi:[1,0]
	v_pk_mul_f32 v[4:5], v[4:5], v[214:215] op_sel_hi:[1,0]
	v_pk_mul_f32 v[2:3], v[2:3], v[214:215] op_sel_hi:[1,0]
	v_mul_f32_e32 v205, v205, v214
	s_branch .LBB0_112
